# GEMM phase cold start: K-tile 1 staging loads issued before the first retire wait (vmcnt 2 -> 8), on top of combined variant
# speedup vs baseline: 1.0097x; 1.0021x over previous
; #define PG8_STAGE(bufoff, gbase, voff) do { _Pragma("unroll") for (int _i = 0; _i < 2; ++_i) \
;         glds16_asm((const char*)(gbase) + (voff)[_i], ldsb + (unsigned)((bufoff) + _i * 8192)); } while (0)
; #define PG8_WAIT_V(n) asm volatile("s_waitcnt vmcnt(" #n ")" ::: "memory")
; #define PG8_BAR __builtin_amdgcn_s_barrier()
; template <class Epi, class Sched, bool ALIGN_EPI = false, bool SP2 = false>
; __device__ __forceinline__ void gemm_phase(PG8_LAS unsigned char* lds, const Gemm g, const Sched& S, const Epi& E, int wave_u) {
;     ...
;     if constexpr (SP2) {
;         PG8_STAGE(PG8_SB(0, 0), cB, voffB); PG8_STAGE(PG8_SB(0, 1), cB + hstep, voffB); PG8_STAGE(PG8_SA(0, 0), cA, voffA); PG8_STAGE(PG8_SA(0, 1), cA + hstep, voffA);
;         if (wr == 1) PG8_BAR;
;         PG8_WAIT_V(2); PG8_BAR;
;         PG8_STAGE(PG8_SB(1, 0), cB + kstep, voffB); PG8_STAGE(PG8_SA(1, 0), cA + kstep, voffA); PG8_STAGE(PG8_SB(1, 1), cB + hstep + kstep, voffB);
;         PG8_WAIT_V(6); PG8_BAR;
.LBB0_137:
	v_readlane_b32 s10, v255, 41
	v_readlane_b32 s11, v255, 42
	v_lshrrev_b32_e32 v131, 1, v130
	s_lshl_b64 s[10:11], s[10:11], 16
	v_readlane_b32 s1, v250, 15
	v_and_b32_e32 v136, 24, v131
	s_add_u32 s18, s1, s10
	v_readlane_b32 s1, v250, 16
	v_and_b32_e32 v198, 15, v130
	v_lshlrev_b32_e32 v131, 1, v136
	v_lshlrev_b32_e32 v130, 2, v130
	s_addc_u32 s19, s1, s11
	s_lshl_b32 s59, s0, 6
	v_lshl_or_b32 v131, v198, 6, v131
	s_lshl_b32 s0, s0, 13
	v_and_b32_e32 v130, 32, v130
	v_bitop3_b32 v137, v131, s0, v130 bitop3:0xde
	s_lshl_b32 s0, s23, 5
	s_and_b32 s10, s0, 0x60
	s_lshl_b32 s0, s10, 7
	v_bitop3_b32 v138, v131, s0, v130 bitop3:0xde
	s_add_u32 s0, s64, 0x80
	s_addc_u32 s1, s65, 0
	s_add_i32 s60, s2, 0x18000
	v_lshl_add_u64 v[130:131], s[0:1], 0, v[172:173]
	s_mov_b32 s11, m0
	s_mov_b32 m0, s60
	s_nop 0
	global_load_lds_dwordx4 v[130:131], off
	s_mov_b32 m0, s11
	v_lshl_add_u64 v[130:131], s[0:1], 0, v[176:177]
	s_add_i32 s61, s2, 0x1a000
	s_mov_b32 s0, m0
	s_mov_b32 m0, s61
	s_nop 0
	global_load_lds_dwordx4 v[130:131], off
	s_mov_b32 m0, s0
	s_add_u32 s0, s88, 0x80
	s_addc_u32 s1, s89, 0
	s_add_i32 s63, s2, 0x8000
	v_lshl_add_u64 v[130:131], s[0:1], 0, v[170:171]
	s_mov_b32 s11, m0
	s_mov_b32 m0, s63
	s_nop 0
	global_load_lds_dwordx4 v[130:131], off
	s_mov_b32 m0, s11
	v_lshl_add_u64 v[130:131], s[0:1], 0, v[174:175]
	s_add_i32 s66, s2, 0xa000
	s_mov_b32 s0, m0
	s_mov_b32 m0, s66
	s_nop 0
	global_load_lds_dwordx4 v[130:131], off
	s_mov_b32 m0, s0
	s_add_u32 s0, s64, 0x40080
	s_addc_u32 s1, s65, 0
	s_add_i32 s67, s2, 0x1c000
	v_lshl_add_u64 v[130:131], s[0:1], 0, v[172:173]
	s_mov_b32 s11, m0
	s_mov_b32 m0, s67
	s_nop 0
	global_load_lds_dwordx4 v[130:131], off
	s_mov_b32 m0, s11
	v_lshl_add_u64 v[130:131], s[0:1], 0, v[176:177]
	s_add_i32 s75, s2, 0x1e000
	s_mov_b32 s0, m0
	s_mov_b32 m0, s75
	s_nop 0
	global_load_lds_dwordx4 v[130:131], off
	s_mov_b32 m0, s0
	s_waitcnt vmcnt(8)
	s_barrier
	s_waitcnt vmcnt(6)
	s_add_i32 s78, s2, 0xc000
	v_or_b32_e32 v0, s59, v198
	v_or_b32_e32 v199, s10, v136
	s_cmpk_lt_u32 s22, 0x100
	v_writelane_b32 v255, s30, 60
	v_or_b32_e32 v200, 0xfffffe00, v199
	s_cselect_b64 s[22:23], -1, 0
	v_lshlrev_b32_e32 v201, 2, v199
	v_lshlrev_b32_e32 v202, 3, v0
	s_add_i32 s79, s2, 0xe000
	s_ashr_i32 s86, s62, 31
	v_lshl_add_u64 v[178:179], v[134:135], 0, v[132:133]
	v_writelane_b32 v255, s31, 61
	v_lshl_add_u64 v[180:181], s[30:31], 0, v[132:133]
	s_mov_b32 s13, 0
	v_add_u32_e32 v203, 0, v138
	v_add_u32_e32 v204, 0, v137
	s_movk_i32 s76, 0x61
	s_movk_i32 s77, 0x3fff
	s_movk_i32 s80, 0x4080
	s_movk_i32 s81, 0x7fd
	s_mov_b64 s[82:83], 0x1000
	s_barrier
	s_branch .LBB0_140

; #define PG8_STAGE(bufoff, gbase, voff) do { _Pragma("unroll") for (int _i = 0; _i < 2; ++_i) \
;         glds16_asm((const char*)(gbase) + (voff)[_i], ldsb + (unsigned)((bufoff) + _i * 8192)); } while (0)
; #define PG8_WAIT_V(n) asm volatile("s_waitcnt vmcnt(" #n ")" ::: "memory")
; #define PG8_BAR __builtin_amdgcn_s_barrier()
; template <class Epi, class Sched, bool ALIGN_EPI = false, bool SP2 = false>
; __device__ __forceinline__ void gemm_phase(PG8_LAS unsigned char* lds, const Gemm g, const Sched& S, const Epi& E, int wave_u) {
;     ...
;     if constexpr (SP2) {
;         PG8_STAGE(PG8_SB(0, 0), cB, voffB); PG8_STAGE(PG8_SB(0, 1), cB + hstep, voffB); PG8_STAGE(PG8_SA(0, 0), cA, voffA); PG8_STAGE(PG8_SA(0, 1), cA + hstep, voffA);
;         if (wr == 1) PG8_BAR;
;         PG8_WAIT_V(2); PG8_BAR;
;         PG8_STAGE(PG8_SB(1, 0), cB + kstep, voffB); PG8_STAGE(PG8_SA(1, 0), cA + kstep, voffA); PG8_STAGE(PG8_SB(1, 1), cB + hstep + kstep, voffB);
;         PG8_WAIT_V(6); PG8_BAR;
.LBB0_258:
	v_readlane_b32 s0, v255, 41
	v_readlane_b32 s1, v255, 42
	s_mov_b32 s16, s0
	v_lshrrev_b32_e32 v127, 1, v126
	s_mul_i32 s1, s16, 0x78000
	v_readlane_b32 s11, v250, 13
	v_and_b32_e32 v132, 24, v127
	s_mul_hi_u32 s0, s0, 0x78000
	s_add_u32 s66, s11, s1
	v_readlane_b32 s1, v250, 14
	v_and_b32_e32 v205, 15, v126
	v_lshlrev_b32_e32 v127, 1, v132
	v_lshlrev_b32_e32 v126, 2, v126
	s_addc_u32 s67, s1, s0
	v_lshl_or_b32 v127, v205, 6, v127
	s_lshl_b32 s0, s10, 13
	v_and_b32_e32 v126, 32, v126
	v_bitop3_b32 v133, v127, s0, v126 bitop3:0xde
	s_lshl_b32 s0, s14, 5
	s_lshl_b32 s85, s10, 6
	s_and_b32 s10, s0, 0x60
	s_lshl_b32 s0, s10, 7
	v_bitop3_b32 v138, v127, s0, v126 bitop3:0xde
	s_add_u32 s0, s64, 0x80
	s_addc_u32 s1, s65, 0
	s_add_i32 s22, s2, 0x18000
	v_lshl_add_u64 v[126:127], s[0:1], 0, v[180:181]
	s_mov_b32 s11, m0
	s_mov_b32 m0, s22
	s_nop 0
	global_load_lds_dwordx4 v[126:127], off
	s_mov_b32 m0, s11
	v_lshl_add_u64 v[126:127], s[0:1], 0, v[184:185]
	s_add_i32 s23, s2, 0x1a000
	s_mov_b32 s0, m0
	s_mov_b32 m0, s23
	s_nop 0
	global_load_lds_dwordx4 v[126:127], off
	s_mov_b32 m0, s0
	s_add_u32 s0, s88, 0x80
	s_addc_u32 s1, s89, 0
	s_add_i32 s24, s2, 0x8000
	v_lshl_add_u64 v[126:127], s[0:1], 0, v[178:179]
	s_mov_b32 s11, m0
	s_mov_b32 m0, s24
	s_nop 0
	global_load_lds_dwordx4 v[126:127], off
	s_mov_b32 m0, s11
	v_lshl_add_u64 v[126:127], s[0:1], 0, v[182:183]
	s_add_i32 s25, s2, 0xa000
	s_mov_b32 s0, m0
	s_mov_b32 m0, s25
	s_nop 0
	global_load_lds_dwordx4 v[126:127], off
	s_mov_b32 m0, s0
	s_add_u32 s0, s64, 0x40080
	s_addc_u32 s1, s65, 0
	s_add_i32 s61, s2, 0x1c000
	v_lshl_add_u64 v[126:127], s[0:1], 0, v[180:181]
	s_mov_b32 s11, m0
	s_mov_b32 m0, s61
	s_nop 0
	global_load_lds_dwordx4 v[126:127], off
	s_mov_b32 m0, s11
	s_add_i32 s26, s2, 0x1e000
	s_add_i32 s27, s2, 0xc000
	v_lshl_add_u64 v[126:127], s[0:1], 0, v[184:185]
	s_mov_b32 s0, m0
	s_mov_b32 m0, s26
	s_nop 0
	global_load_lds_dwordx4 v[126:127], off
	s_mov_b32 m0, s0
	s_cmpk_lt_u32 s7, 0x100
	s_cselect_b64 s[0:1], -1, 0
	v_writelane_b32 v255, s0, 57
	s_waitcnt vmcnt(8)
	s_barrier
	s_waitcnt vmcnt(6)
	v_or_b32_e32 v0, s85, v205
	v_or_b32_e32 v207, s10, v132
	v_writelane_b32 v255, s1, 58
	s_ashr_i32 s0, s62, 31
	v_writelane_b32 v255, s0, 59
	v_writelane_b32 v255, s30, 60
	v_or_b32_e32 v208, 0xfffffc00, v207
	v_lshlrev_b32_e32 v209, 2, v207
	v_writelane_b32 v255, s31, 61
	v_lshlrev_b32_e32 v210, 3, v0
	v_readlane_b32 s82, v255, 53
	s_add_i32 s60, s2, 0xe000
	v_lshl_add_u64 v[186:187], v[130:131], 0, v[128:129]
	v_lshl_add_u64 v[188:189], s[30:31], 0, v[128:129]
	s_mov_b32 s7, 0
	v_add_u32_e32 v211, 0, v138
	v_add_u32_e32 v212, 0, v133
	s_movk_i32 s76, 0x61
	s_movk_i32 s77, 0x3fff
	s_movk_i32 s78, 0x4080
	s_movk_i32 s79, 0x7e1
	s_mov_b64 s[80:81], 0xe800
	v_readlane_b32 s83, v255, 54
	s_barrier
	s_branch .LBB0_261

; #define PG8_STAGE(bufoff, gbase, voff) do { _Pragma("unroll") for (int _i = 0; _i < 2; ++_i) \
;         glds16_asm((const char*)(gbase) + (voff)[_i], ldsb + (unsigned)((bufoff) + _i * 8192)); } while (0)
; #define PG8_WAIT_V(n) asm volatile("s_waitcnt vmcnt(" #n ")" ::: "memory")
; #define PG8_BAR __builtin_amdgcn_s_barrier()
; template <class Epi, class Sched, bool ALIGN_EPI = false, bool SP2 = false>
; __device__ __forceinline__ void gemm_phase(PG8_LAS unsigned char* lds, const Gemm g, const Sched& S, const Epi& E, int wave_u) {
;     ...
;     if constexpr (SP2) {
;         PG8_STAGE(PG8_SB(0, 0), cB, voffB); PG8_STAGE(PG8_SB(0, 1), cB + hstep, voffB); PG8_STAGE(PG8_SA(0, 0), cA, voffA); PG8_STAGE(PG8_SA(0, 1), cA + hstep, voffA);
;         if (wr == 1) PG8_BAR;
;         PG8_WAIT_V(2); PG8_BAR;
;         PG8_STAGE(PG8_SB(1, 0), cB + kstep, voffB); PG8_STAGE(PG8_SA(1, 0), cA + kstep, voffA); PG8_STAGE(PG8_SB(1, 1), cB + hstep + kstep, voffB);
;         PG8_WAIT_V(6); PG8_BAR;
.LBB0_970:
	v_bfe_u32 v0, v50, 4, 2
	v_and_b32_e32 v51, 15, v50
	v_lshlrev_b32_e32 v64, 4, v0
	v_lshlrev_b32_e32 v50, 2, v50
	v_lshl_or_b32 v223, s0, 6, v51
	v_lshl_or_b32 v51, v51, 6, v64
	s_lshl_b32 s0, s0, 13
	v_and_b32_e32 v50, 32, v50
	v_bitop3_b32 v64, v51, s0, v50 bitop3:0xde
	s_lshl_b32 s0, s7, 5
	s_and_b32 s10, s0, 0x60
	s_lshl_b32 s0, s10, 7
	v_bitop3_b32 v65, v51, s0, v50 bitop3:0xde
	s_add_u32 s0, s60, 0x80
	s_addc_u32 s1, s61, 0
	s_add_i32 s90, s2, 0x18000
	v_lshl_add_u64 v[50:51], s[0:1], 0, v[200:201]
	s_mov_b32 s7, m0
	s_mov_b32 m0, s90
	s_nop 0
	global_load_lds_dwordx4 v[50:51], off
	s_mov_b32 m0, s7
	v_lshl_add_u64 v[50:51], s[0:1], 0, v[204:205]
	s_add_i32 s91, s2, 0x1a000
	s_mov_b32 s0, m0
	s_mov_b32 m0, s91
	s_nop 0
	global_load_lds_dwordx4 v[50:51], off
	s_mov_b32 m0, s0
	s_add_u32 s0, s64, 0x80
	s_addc_u32 s1, s65, 0
	s_add_i32 s40, s2, 0x8000
	v_lshl_add_u64 v[50:51], s[0:1], 0, v[198:199]
	s_mov_b32 s7, m0
	s_mov_b32 m0, s40
	s_nop 0
	global_load_lds_dwordx4 v[50:51], off
	s_mov_b32 m0, s7
	v_lshl_add_u64 v[50:51], s[0:1], 0, v[202:203]
	s_add_i32 s41, s2, 0xa000
	s_mov_b32 s0, m0
	s_mov_b32 m0, s41
	s_nop 0
	global_load_lds_dwordx4 v[50:51], off
	s_mov_b32 m0, s0
	s_add_u32 s0, s60, 0x40080
	s_addc_u32 s1, s61, 0
	s_add_i32 s66, s2, 0x1c000
	v_lshl_add_u64 v[50:51], s[0:1], 0, v[200:201]
	s_mov_b32 s7, m0
	s_mov_b32 m0, s66
	s_nop 0
	global_load_lds_dwordx4 v[50:51], off
	s_mov_b32 m0, s7
	v_lshl_add_u64 v[50:51], s[0:1], 0, v[204:205]
	s_add_i32 s67, s2, 0x1e000
	s_mov_b32 s0, m0
	s_mov_b32 m0, s67
	s_nop 0
	global_load_lds_dwordx4 v[50:51], off
	s_mov_b32 m0, s0
	s_waitcnt vmcnt(8)
	s_barrier
	s_waitcnt vmcnt(6)
	s_add_i32 s7, s2, 0xc000
	s_cmpk_lt_u32 s20, 0x100
	v_lshl_or_b32 v224, v0, 3, s10
	s_cselect_b64 s[16:17], -1, 0
	s_mov_b32 s27, 0
	v_cmp_eq_u32_e64 s[10:11], 0, v0
	v_lshlrev_b32_e32 v225, 3, v223
	v_lshlrev_b32_e32 v226, 2, v224
	s_add_i32 s75, s2, 0xe000
	s_ashr_i32 s78, s58, 31
	v_lshl_add_u64 v[206:207], v[62:63], 0, v[52:53]
	v_lshl_add_u64 v[208:209], s[12:13], 0, v[52:53]
	v_add_u32_e32 v227, 0, v65
	v_add_u32_e32 v228, 0, v64
	s_barrier
	s_branch .LBB0_973

; #define PG8_STAGE(bufoff, gbase, voff) do { _Pragma("unroll") for (int _i = 0; _i < 2; ++_i) \
;         glds16_asm((const char*)(gbase) + (voff)[_i], ldsb + (unsigned)((bufoff) + _i * 8192)); } while (0)
; #define PG8_WAIT_V(n) asm volatile("s_waitcnt vmcnt(" #n ")" ::: "memory")
; #define PG8_BAR __builtin_amdgcn_s_barrier()
; template <class Epi, class Sched, bool ALIGN_EPI = false, bool SP2 = false>
; __device__ __forceinline__ void gemm_phase(PG8_LAS unsigned char* lds, const Gemm g, const Sched& S, const Epi& E, int wave_u) {
;     ...
;     if constexpr (SP2) {
;         PG8_STAGE(PG8_SB(0, 0), cB, voffB); PG8_STAGE(PG8_SB(0, 1), cB + hstep, voffB); PG8_STAGE(PG8_SA(0, 0), cA, voffA); PG8_STAGE(PG8_SA(0, 1), cA + hstep, voffA);
;         if (wr == 1) PG8_BAR;
;         PG8_WAIT_V(2); PG8_BAR;
;         PG8_STAGE(PG8_SB(1, 0), cB + kstep, voffB); PG8_STAGE(PG8_SA(1, 0), cA + kstep, voffA); PG8_STAGE(PG8_SB(1, 1), cB + hstep + kstep, voffB);
;         PG8_WAIT_V(6); PG8_BAR;
.LBB0_1169:
	v_lshrrev_b32_e32 v136, 1, v130
	v_and_b32_e32 v131, 15, v130
	v_and_b32_e32 v136, 24, v136
	s_lshl_b32 s0, s0, 5
	v_lshl_or_b32 v0, s11, 6, v131
	v_lshlrev_b32_e32 v137, 1, v136
	s_lshl_b32 s1, s11, 13
	v_lshlrev_b32_e32 v130, 2, v130
	s_and_b32 s11, s0, 0x60
	v_lshl_or_b32 v131, v131, 6, v137
	v_and_b32_e32 v130, 32, v130
	s_lshl_b32 s0, s11, 7
	v_bitop3_b32 v138, v131, s0, v130 bitop3:0xde
	s_add_u32 s0, s34, 0x80
	v_bitop3_b32 v137, v131, s1, v130 bitop3:0xde
	s_addc_u32 s1, s35, 0
	s_add_i32 s66, s7, 0x18000
	v_lshl_add_u64 v[130:131], s[0:1], 0, v[166:167]
	s_mov_b32 s18, m0
	s_mov_b32 m0, s66
	s_nop 0
	global_load_lds_dwordx4 v[130:131], off
	s_mov_b32 m0, s18
	v_lshl_add_u64 v[130:131], s[0:1], 0, v[162:163]
	s_add_i32 s67, s7, 0x1a000
	s_mov_b32 s0, m0
	s_mov_b32 m0, s67
	s_nop 0
	global_load_lds_dwordx4 v[130:131], off
	s_mov_b32 m0, s0
	s_add_u32 s0, s60, 0x80
	s_addc_u32 s1, s61, 0
	s_add_i32 s75, s7, 0x8000
	v_lshl_add_u64 v[130:131], s[0:1], 0, v[168:169]
	s_mov_b32 s18, m0
	s_mov_b32 m0, s75
	s_nop 0
	global_load_lds_dwordx4 v[130:131], off
	s_mov_b32 m0, s18
	v_lshl_add_u64 v[130:131], s[0:1], 0, v[164:165]
	s_add_i32 s78, s7, 0xa000
	s_mov_b32 s0, m0
	s_mov_b32 m0, s78
	s_nop 0
	global_load_lds_dwordx4 v[130:131], off
	s_mov_b32 m0, s0
	s_add_u32 s0, s34, 0x40080
	s_addc_u32 s1, s35, 0
	s_add_i32 s79, s7, 0x1c000
	v_lshl_add_u64 v[130:131], s[0:1], 0, v[166:167]
	s_mov_b32 s18, m0
	s_mov_b32 m0, s79
	s_nop 0
	global_load_lds_dwordx4 v[130:131], off
	s_mov_b32 m0, s18
	v_lshl_add_u64 v[130:131], s[0:1], 0, v[162:163]
	s_add_i32 s86, s7, 0x1e000
	s_mov_b32 s0, m0
	s_mov_b32 m0, s86
	s_nop 0
	global_load_lds_dwordx4 v[130:131], off
	s_mov_b32 m0, s0
	s_waitcnt vmcnt(8)
	s_barrier
	s_waitcnt vmcnt(6)
	s_add_i32 s87, s7, 0xc000
	s_cmpk_lt_u32 s10, 0x100
	v_or_b32_e32 v174, s11, v136
	s_cselect_b64 s[18:19], -1, 0
	v_lshlrev_b32_e32 v175, 2, v174
	v_lshlrev_b32_e32 v176, 3, v0
	s_add_i32 s88, s7, 0xe000
	v_lshl_add_u64 v[170:171], v[134:135], 0, v[132:133]
	v_lshl_add_u64 v[172:173], s[28:29], 0, v[132:133]
	s_mov_b32 s31, 0
	v_add_u32_e32 v177, 0, v138
	v_add_u32_e32 v178, 0, v137
	s_barrier
	s_branch .LBB0_1172

; #define PG8_STAGE(bufoff, gbase, voff) do { _Pragma("unroll") for (int _i = 0; _i < 2; ++_i) \
;         glds16_asm((const char*)(gbase) + (voff)[_i], ldsb + (unsigned)((bufoff) + _i * 8192)); } while (0)
; #define PG8_WAIT_V(n) asm volatile("s_waitcnt vmcnt(" #n ")" ::: "memory")
; #define PG8_BAR __builtin_amdgcn_s_barrier()
; template <class Epi, class Sched, bool ALIGN_EPI = false, bool SP2 = false>
; __device__ __forceinline__ void gemm_phase(PG8_LAS unsigned char* lds, const Gemm g, const Sched& S, const Epi& E, int wave_u) {
;     ...
;     if constexpr (SP2) {
;         PG8_STAGE(PG8_SB(0, 0), cB, voffB); PG8_STAGE(PG8_SB(0, 1), cB + hstep, voffB); PG8_STAGE(PG8_SA(0, 0), cA, voffA); PG8_STAGE(PG8_SA(0, 1), cA + hstep, voffA);
;         if (wr == 1) PG8_BAR;
;         PG8_WAIT_V(2); PG8_BAR;
;         PG8_STAGE(PG8_SB(1, 0), cB + kstep, voffB); PG8_STAGE(PG8_SA(1, 0), cA + kstep, voffA); PG8_STAGE(PG8_SB(1, 1), cB + hstep + kstep, voffB);
;         PG8_WAIT_V(6); PG8_BAR;
.LBB0_1414:
	v_bfe_u32 v0, v50, 4, 2
	v_and_b32_e32 v51, 15, v50
	v_lshlrev_b32_e32 v64, 4, v0
	v_lshlrev_b32_e32 v50, 2, v50
	v_lshl_or_b32 v223, s0, 6, v51
	v_lshl_or_b32 v51, v51, 6, v64
	s_lshl_b32 s0, s0, 13
	v_and_b32_e32 v50, 32, v50
	v_bitop3_b32 v64, v51, s0, v50 bitop3:0xde
	s_lshl_b32 s0, s7, 5
	s_and_b32 s10, s0, 0x60
	s_lshl_b32 s0, s10, 7
	v_bitop3_b32 v65, v51, s0, v50 bitop3:0xde
	s_add_u32 s0, s60, 0x80
	s_addc_u32 s1, s61, 0
	s_add_i32 s62, s84, 0x18000
	v_lshl_add_u64 v[50:51], s[0:1], 0, v[200:201]
	s_mov_b32 s7, m0
	s_mov_b32 m0, s62
	s_nop 0
	global_load_lds_dwordx4 v[50:51], off
	s_mov_b32 m0, s7
	v_lshl_add_u64 v[50:51], s[0:1], 0, v[204:205]
	s_add_i32 s63, s84, 0x1a000
	s_mov_b32 s0, m0
	s_mov_b32 m0, s63
	s_nop 0
	global_load_lds_dwordx4 v[50:51], off
	s_mov_b32 m0, s0
	s_add_u32 s0, s64, 0x80
	s_addc_u32 s1, s65, 0
	s_add_i32 s40, s84, 0x8000
	v_lshl_add_u64 v[50:51], s[0:1], 0, v[198:199]
	s_mov_b32 s7, m0
	s_mov_b32 m0, s40
	s_nop 0
	global_load_lds_dwordx4 v[50:51], off
	s_mov_b32 m0, s7
	v_lshl_add_u64 v[50:51], s[0:1], 0, v[202:203]
	s_add_i32 s41, s84, 0xa000
	s_mov_b32 s0, m0
	s_mov_b32 m0, s41
	s_nop 0
	global_load_lds_dwordx4 v[50:51], off
	s_mov_b32 m0, s0
	s_add_u32 s0, s60, 0xb0080
	s_addc_u32 s1, s61, 0
	s_add_i32 s66, s84, 0x1c000
	v_lshl_add_u64 v[50:51], s[0:1], 0, v[200:201]
	s_mov_b32 s7, m0
	s_mov_b32 m0, s66
	s_nop 0
	global_load_lds_dwordx4 v[50:51], off
	s_mov_b32 m0, s7
	v_lshl_add_u64 v[50:51], s[0:1], 0, v[204:205]
	s_add_i32 s67, s84, 0x1e000
	s_mov_b32 s0, m0
	s_mov_b32 m0, s67
	s_nop 0
	global_load_lds_dwordx4 v[50:51], off
	s_mov_b32 m0, s0
	s_waitcnt vmcnt(8)
	s_barrier
	s_waitcnt vmcnt(6)
	s_add_i32 s7, s84, 0xc000
	s_cmpk_lt_u32 s18, 0x100
	v_lshl_or_b32 v224, v0, 3, s10
	s_cselect_b64 s[18:19], -1, 0
	s_mov_b32 s79, 0
	v_cmp_eq_u32_e64 s[10:11], 0, v0
	v_lshlrev_b32_e32 v225, 3, v223
	v_lshlrev_b32_e32 v226, 2, v224
	s_add_i32 s75, s84, 0xe000
	s_ashr_i32 s78, s2, 31
	v_lshl_add_u64 v[206:207], v[62:63], 0, v[52:53]
	v_lshl_add_u64 v[208:209], s[28:29], 0, v[52:53]
	v_add_u32_e32 v227, 0, v65
	v_add_u32_e32 v228, 0, v64
	s_barrier
	s_branch .LBB0_1417
